# GEMM2/GEMM4 entry stagger of the second resident block shortened from s_sleep 127 to s_sleep 40
# baseline (speedup 1.0000x reference)
.LBB0_140:
	s_andn2_b64 vcc, exec, s[0:1]
	s_cbranch_vccnz .LBB0_152
	s_bitcmp1_b32 s91, 8
	s_cbranch_scc0 .Lgs4_nostag
	s_sleep 40
